# strategy 9 (7.12): deleted the self-max canonicalisation pairs behind each permlane swap in the softmax row-max chains (exact no-ops)
# speedup vs baseline: 1.0124x; 1.0040x over previous
; DI float ex2(float x) { return __builtin_amdgcn_exp2f(x); }
; #define SB0 __builtin_amdgcn_sched_barrier(0)
; template <bool MASKED, class MF>
; DI void flash_update(f32x4 (&s)[4], float scl, float& mx, float& ls, f32x4 (&o)[8], MF maskfn, bool lane_on) {
;   float tmax = -1e30f;
; #pragma unroll
;   for (int kt = 0; kt < 4; ++kt)
; #pragma unroll
;     for (int i = 0; i < 4; ++i) {
;       if (MASKED) { if (maskfn(kt, i)) s[kt][i] = -1e30f; }
;       tmax = fmaxf(tmax, s[kt][i]);
;     }
;   tmax = rowmax4(tmax);
;   if (!lane_on) tmax = -1e30f;
;   const float th = 8.f / scl;
;   if (__any(tmax > mx + th)) {
;     const float mnew = fmaxf(mx, tmax);
;     const float alpha = ex2((mx - mnew) * scl);
;     ls *= alpha;
; #pragma unroll
;     for (int dt = 0; dt < 8; ++dt) o[dt] *= alpha;
;     mx = mnew;
;   }
; DI void diff_S2(f32x4 (&s0)[4], f32x4 (&s1)[4], const char* Kb, const char* Vb, int m, const bf16x8 (&q0)[2], const bf16x8 (&q1)[2],
;                 bf16x8 (&v0)[4], bf16x8 (&v1)[4], int lr, int quad) {
;   bf16x8 f0[2], f1[2], f2[2], f3[2];
;   ldk2m(f0, Kb, m, 0, lr, quad); ldk2m(f1, Kb, m, 1, lr, quad); SB0;
;   ldk2m(f2, Kb, m, 2, lr, quad); s0[0] = mma2(f0, q0); s1[0] = mma2(f0, q1); SB0;
;   ldk2m(f3, Kb, m, 3, lr, quad); s0[1] = mma2(f1, q0); s1[1] = mma2(f1, q1); SB0;
;   ldv4(v0, Vb, 0, lr, quad); s0[2] = mma2(f2, q0); s1[2] = mma2(f2, q1); SB0;
;   ldv4(v1, Vb, 1, lr, quad); s0[3] = mma2(f3, q0); s1[3] = mma2(f3, q1); SB0;
; }
.LBB0_571:
	s_cmp_eq_u32 s7, s63
	s_cbranch_scc1 .LBB0_582
	s_or_b32 s4, s7, s65
	s_lshl_b32 s6, s4, 6
	v_cmp_le_u32_e32 vcc, s6, v211
	s_and_saveexec_b64 s[48:49], vcc
	s_cbranch_execz .LBB0_570
	s_lshl_b32 s4, s7, 15
	s_add_i32 s67, s66, s4
	v_add_u32_e32 v0, s67, v212
	v_add_u32_e32 v28, v0, v214
	v_add_u32_e32 v29, v0, v215
	ds_read_b128 v[0:3], v28
	ds_read_b128 v[4:7], v28 offset:4096
	ds_read_b128 v[8:11], v29
	ds_read_b128 v[12:15], v29 offset:4096
	s_or_b32 s4, s6, 63
	v_cmp_le_u32_e32 vcc, s4, v207
	ds_read_b128 v[16:19], v28 offset:8192
	ds_read_b128 v[20:23], v29 offset:8192
	s_waitcnt lgkmcnt(5)
	v_mfma_f32_16x16x32_bf16 v[24:27], v[0:3], v[96:99], 0
	s_waitcnt lgkmcnt(3)
	v_mfma_f32_16x16x32_bf16 v[172:175], v[8:11], v[100:103], v[24:27]
	s_nop 0
	v_mfma_f32_16x16x32_bf16 v[0:3], v[0:3], v[104:107], 0
	v_mfma_f32_16x16x32_bf16 v[156:159], v[8:11], v[108:111], v[0:3]
	s_nop 0
	s_nop 5
	ds_read_b128 v[0:3], v28 offset:12288
	ds_read_b128 v[8:11], v29 offset:12288
	v_mfma_f32_16x16x32_bf16 v[24:27], v[4:7], v[96:99], 0
	s_waitcnt lgkmcnt(4)
	v_mfma_f32_16x16x32_bf16 v[164:167], v[12:15], v[100:103], v[24:27]
	s_nop 0
	v_mfma_f32_16x16x32_bf16 v[4:7], v[4:7], v[104:107], 0
	v_mfma_f32_16x16x32_bf16 v[148:151], v[12:15], v[108:111], v[4:7]
	s_nop 0
	v_add3_u32 v12, s67, v217, v216
	ds_read_b128 v[140:143], v12 offset:16384
	ds_read_b128 v[136:139], v12 offset:18432
	ds_read_b128 v[128:131], v12 offset:20480
	ds_read_b128 v[120:123], v12 offset:22528
	s_waitcnt lgkmcnt(7)
	v_mfma_f32_16x16x32_bf16 v[4:7], v[16:19], v[96:99], 0
	s_waitcnt lgkmcnt(6)
	v_mfma_f32_16x16x32_bf16 v[168:171], v[20:23], v[100:103], v[4:7]
	s_nop 0
	v_mfma_f32_16x16x32_bf16 v[4:7], v[16:19], v[104:107], 0
	v_mfma_f32_16x16x32_bf16 v[152:155], v[20:23], v[108:111], v[4:7]
	s_nop 0
	ds_read_b128 v[132:135], v12 offset:24576
	ds_read_b128 v[124:127], v12 offset:26624
	ds_read_b128 v[116:119], v12 offset:28672
	ds_read_b128 v[112:115], v12 offset:30720
	s_waitcnt lgkmcnt(9)
	v_mfma_f32_16x16x32_bf16 v[4:7], v[0:3], v[96:99], 0
	s_waitcnt lgkmcnt(8)
	v_mfma_f32_16x16x32_bf16 v[160:163], v[8:11], v[100:103], v[4:7]
	s_nop 0
	v_mfma_f32_16x16x32_bf16 v[0:3], v[0:3], v[104:107], 0
	v_mfma_f32_16x16x32_bf16 v[144:147], v[8:11], v[108:111], v[0:3]
	s_nop 0
	v_add_f32_e32 v232, 0x40b17218, v220
	s_and_saveexec_b64 s[4:5], vcc
	s_xor_b64 s[4:5], exec, s[4:5]
	s_cbranch_execz .LBB0_579
	s_nop 1
	v_max3_f32 v0, v172, s53, v173
	v_max3_f32 v0, v0, v174, v175
	v_max3_f32 v0, v0, v164, v165
	v_max3_f32 v0, v0, v166, v167
	v_max3_f32 v0, v0, v168, v169
	v_max3_f32 v0, v0, v170, v171
	v_max3_f32 v0, v0, v160, v161
	v_max3_f32 v0, v0, v162, v163
	v_mov_b32_e32 v1, v0
	s_nop 1
	v_permlane16_swap_b32_e32 v0, v1
	v_max_f32_e32 v0, v0, v1
	v_mov_b32_e32 v1, v0
	s_nop 1
	v_permlane32_swap_b32_e32 v0, v1
	v_max_f32_e32 v0, v0, v1
	v_cmp_gt_f32_e32 vcc, v0, v232
	s_cbranch_vccz .LBB0_576
	v_max_f32_e32 v0, v0, v0
	v_max_f32_e32 v1, v220, v220
	v_max_f32_e32 v1, v1, v0
	v_sub_f32_e32 v0, v220, v1
	v_mul_f32_e32 v0, 0x3fb8aa3b, v0
	v_exp_f32_e32 v0, v0
	v_mov_b32_e32 v220, v1
	v_mul_f32_e32 v213, v213, v0
	v_pk_mul_f32 v[94:95], v[94:95], v[0:1] op_sel_hi:[1,0]
	v_pk_mul_f32 v[92:93], v[92:93], v[0:1] op_sel_hi:[1,0]
	v_pk_mul_f32 v[90:91], v[90:91], v[0:1] op_sel_hi:[1,0]
	v_pk_mul_f32 v[88:89], v[88:89], v[0:1] op_sel_hi:[1,0]
	v_pk_mul_f32 v[86:87], v[86:87], v[0:1] op_sel_hi:[1,0]
	v_pk_mul_f32 v[84:85], v[84:85], v[0:1] op_sel_hi:[1,0]
	v_pk_mul_f32 v[82:83], v[82:83], v[0:1] op_sel_hi:[1,0]
	v_pk_mul_f32 v[80:81], v[80:81], v[0:1] op_sel_hi:[1,0]
	v_pk_mul_f32 v[78:79], v[78:79], v[0:1] op_sel_hi:[1,0]
	v_pk_mul_f32 v[76:77], v[76:77], v[0:1] op_sel_hi:[1,0]
	v_pk_mul_f32 v[74:75], v[74:75], v[0:1] op_sel_hi:[1,0]
	v_pk_mul_f32 v[72:73], v[72:73], v[0:1] op_sel_hi:[1,0]
	v_pk_mul_f32 v[70:71], v[70:71], v[0:1] op_sel_hi:[1,0]
	v_pk_mul_f32 v[68:69], v[68:69], v[0:1] op_sel_hi:[1,0]
	v_pk_mul_f32 v[66:67], v[66:67], v[0:1] op_sel_hi:[1,0]
	v_pk_mul_f32 v[64:65], v[64:65], v[0:1] op_sel_hi:[1,0]
.LBB0_576:
	v_max3_f32 v0, v156, s53, v157
	v_max3_f32 v0, v0, v158, v159
	v_max3_f32 v0, v0, v148, v149
	v_max3_f32 v0, v0, v150, v151
	v_max3_f32 v0, v0, v152, v153
	v_max3_f32 v0, v0, v154, v155
	v_max3_f32 v0, v0, v144, v145
	v_max3_f32 v0, v0, v146, v147
	v_mov_b32_e32 v1, v0
	s_nop 1
	v_permlane16_swap_b32_e32 v0, v1
	v_max_f32_e32 v0, v0, v1
	v_mov_b32_e32 v1, v0
	s_nop 1
	v_permlane32_swap_b32_e32 v0, v1
	v_max_f32_e32 v0, v0, v1
	v_add_f32_e32 v1, 0x40b17218, v221
	v_cmp_gt_f32_e32 vcc, v0, v1
	s_cbranch_vccz .LBB0_578
	v_max_f32_e32 v0, v0, v0
	v_max_f32_e32 v1, v221, v221
	v_max_f32_e32 v1, v1, v0
	v_sub_f32_e32 v0, v221, v1
	v_mul_f32_e32 v0, 0x3fb8aa3b, v0
	v_exp_f32_e32 v0, v0
	v_mov_b32_e32 v221, v1
	v_mul_f32_e32 v219, v219, v0
	v_pk_mul_f32 v[62:63], v[62:63], v[0:1] op_sel_hi:[1,0]
	v_pk_mul_f32 v[60:61], v[60:61], v[0:1] op_sel_hi:[1,0]
	v_pk_mul_f32 v[58:59], v[58:59], v[0:1] op_sel_hi:[1,0]
	v_pk_mul_f32 v[56:57], v[56:57], v[0:1] op_sel_hi:[1,0]
	v_pk_mul_f32 v[54:55], v[54:55], v[0:1] op_sel_hi:[1,0]
	v_pk_mul_f32 v[52:53], v[52:53], v[0:1] op_sel_hi:[1,0]
	v_pk_mul_f32 v[50:51], v[50:51], v[0:1] op_sel_hi:[1,0]
	v_pk_mul_f32 v[48:49], v[48:49], v[0:1] op_sel_hi:[1,0]
	v_pk_mul_f32 v[46:47], v[46:47], v[0:1] op_sel_hi:[1,0]
	v_pk_mul_f32 v[44:45], v[44:45], v[0:1] op_sel_hi:[1,0]
	v_pk_mul_f32 v[42:43], v[42:43], v[0:1] op_sel_hi:[1,0]
	v_pk_mul_f32 v[40:41], v[40:41], v[0:1] op_sel_hi:[1,0]
	v_pk_mul_f32 v[38:39], v[38:39], v[0:1] op_sel_hi:[1,0]
	v_pk_mul_f32 v[36:37], v[36:37], v[0:1] op_sel_hi:[1,0]
	v_pk_mul_f32 v[34:35], v[34:35], v[0:1] op_sel_hi:[1,0]
	v_pk_mul_f32 v[32:33], v[32:33], v[0:1] op_sel_hi:[1,0]

; DI float ex2(float x) { return __builtin_amdgcn_exp2f(x); }
; template <bool MASKED, class MF>
; DI void flash_update(f32x4 (&s)[4], float scl, float& mx, float& ls, f32x4 (&o)[8], MF maskfn, bool lane_on) {
;   float tmax = -1e30f;
; #pragma unroll
;   for (int kt = 0; kt < 4; ++kt)
; #pragma unroll
;     for (int i = 0; i < 4; ++i) {
;       if (MASKED) { if (maskfn(kt, i)) s[kt][i] = -1e30f; }
;       tmax = fmaxf(tmax, s[kt][i]);
;     }
;   tmax = rowmax4(tmax);
;   if (!lane_on) tmax = -1e30f;
;   const float th = 8.f / scl;
;   if (__any(tmax > mx + th)) {
;     const float mnew = fmaxf(mx, tmax);
;     const float alpha = ex2((mx - mnew) * scl);
;     ls *= alpha;
; #pragma unroll
;     for (int dt = 0; dt < 8; ++dt) o[dt] *= alpha;
;     mx = mnew;
;   }
.LBB0_579:
	s_andn2_saveexec_b64 s[50:51], s[4:5]
	s_cbranch_execz .LBB0_569
	v_or_b32_e32 v16, s6, v181
	v_cmp_gt_u32_e64 s[4:5], v16, v208
	v_cmp_lt_u32_e32 vcc, v16, v208
	v_or_b32_e32 v18, 2, v16
	v_or_b32_e32 v19, 3, v16
	v_cndmask_b32_e64 v17, v172, v195, s[4:5]
	v_cndmask_b32_e32 v1, v195, v173, vcc
	v_cmp_gt_u32_e64 s[6:7], v18, v208
	v_cmp_gt_u32_e64 s[8:9], v19, v208
	v_max3_f32 v4, v17, s53, v1
	v_cndmask_b32_e64 v2, v174, v195, s[6:7]
	v_cndmask_b32_e64 v3, v175, v195, s[8:9]
	v_max3_f32 v6, v4, v2, v3
	v_or_b32_e32 v4, 16, v16
	v_cndmask_b32_e32 v0, v17, v172, vcc
	v_cmp_le_u32_e32 vcc, v4, v208
	v_or_b32_e32 v21, 17, v16
	v_or_b32_e32 v22, 18, v16
	v_cndmask_b32_e32 v4, v195, v164, vcc
	v_cmp_gt_u32_e32 vcc, v21, v208
	v_or_b32_e32 v23, 19, v16
	v_cmp_gt_u32_e64 s[10:11], v23, v208
	v_cndmask_b32_e32 v5, v165, v195, vcc
	v_cmp_gt_u32_e32 vcc, v22, v208
	v_or_b32_e32 v24, 32, v16
	v_max3_f32 v8, v6, v4, v5
	v_cndmask_b32_e32 v6, v166, v195, vcc
	v_cndmask_b32_e64 v7, v167, v195, s[10:11]
	v_cmp_le_u32_e32 vcc, v24, v208
	v_or_b32_e32 v25, 33, v16
	v_max3_f32 v10, v8, v6, v7
	v_cndmask_b32_e32 v8, v195, v168, vcc
	v_cmp_gt_u32_e32 vcc, v25, v208
	v_or_b32_e32 v26, 34, v16
	v_or_b32_e32 v27, 35, v16
	v_cndmask_b32_e32 v9, v169, v195, vcc
	v_cmp_gt_u32_e32 vcc, v26, v208
	v_cmp_gt_u32_e64 s[12:13], v27, v208
	v_or_b32_e32 v28, 48, v16
	v_max3_f32 v12, v10, v8, v9
	v_cndmask_b32_e32 v10, v170, v195, vcc
	v_cndmask_b32_e64 v11, v171, v195, s[12:13]
	v_cmp_le_u32_e32 vcc, v28, v208
	v_or_b32_e32 v29, 49, v16
	v_max3_f32 v14, v12, v10, v11
	v_cndmask_b32_e32 v12, v195, v160, vcc
	v_cmp_gt_u32_e32 vcc, v29, v208
	v_or_b32_e32 v30, 50, v16
	v_or_b32_e32 v31, 51, v16
	v_cndmask_b32_e32 v13, v161, v195, vcc
	v_cmp_gt_u32_e32 vcc, v30, v208
	v_cmp_gt_u32_e64 s[14:15], v31, v208
	v_max3_f32 v20, v14, v12, v13
	v_cndmask_b32_e32 v14, v162, v195, vcc
	v_cndmask_b32_e64 v15, v163, v195, s[14:15]
	v_max3_f32 v20, v20, v14, v15
	v_mov_b32_e32 v160, v20
	s_nop 1
	v_permlane16_swap_b32_e32 v20, v160
	v_max_f32_e32 v20, v20, v160
	v_mov_b32_e32 v160, v20
	s_nop 1
	v_permlane32_swap_b32_e32 v20, v160
	v_max_f32_e32 v20, v20, v160
	v_cmp_gt_f32_e32 vcc, v20, v232
	s_cbranch_vccz .LBB0_583
	v_max_f32_e32 v7, v20, v20
	v_max_f32_e32 v11, v220, v220
	v_max_f32_e32 v17, v11, v7
	v_sub_f32_e32 v7, v220, v17
	v_mul_f32_e32 v7, 0x3fb8aa3b, v7
	v_exp_f32_e32 v20, v7
	v_cndmask_b32_e64 v3, v175, v195, s[8:9]
	v_cndmask_b32_e64 v7, v167, v195, s[10:11]
	v_cndmask_b32_e64 v11, v171, v195, s[12:13]
	v_cndmask_b32_e64 v15, v163, v195, s[14:15]
	v_mul_f32_e32 v213, v213, v20
	v_pk_mul_f32 v[94:95], v[94:95], v[20:21] op_sel_hi:[1,0]
	v_pk_mul_f32 v[92:93], v[92:93], v[20:21] op_sel_hi:[1,0]
	v_pk_mul_f32 v[90:91], v[90:91], v[20:21] op_sel_hi:[1,0]
	v_pk_mul_f32 v[88:89], v[88:89], v[20:21] op_sel_hi:[1,0]
	v_pk_mul_f32 v[86:87], v[86:87], v[20:21] op_sel_hi:[1,0]
	v_pk_mul_f32 v[84:85], v[84:85], v[20:21] op_sel_hi:[1,0]
	v_pk_mul_f32 v[82:83], v[82:83], v[20:21] op_sel_hi:[1,0]
	v_pk_mul_f32 v[80:81], v[80:81], v[20:21] op_sel_hi:[1,0]
	v_pk_mul_f32 v[78:79], v[78:79], v[20:21] op_sel_hi:[1,0]
	v_pk_mul_f32 v[76:77], v[76:77], v[20:21] op_sel_hi:[1,0]
	v_pk_mul_f32 v[74:75], v[74:75], v[20:21] op_sel_hi:[1,0]
	v_pk_mul_f32 v[72:73], v[72:73], v[20:21] op_sel_hi:[1,0]
	v_pk_mul_f32 v[70:71], v[70:71], v[20:21] op_sel_hi:[1,0]
	v_pk_mul_f32 v[68:69], v[68:69], v[20:21] op_sel_hi:[1,0]
	v_pk_mul_f32 v[66:67], v[66:67], v[20:21] op_sel_hi:[1,0]
	v_pk_mul_f32 v[64:65], v[64:65], v[20:21] op_sel_hi:[1,0]
	v_mov_b32_e32 v220, v17
	s_branch .LBB0_584

; DI float ex2(float x) { return __builtin_amdgcn_exp2f(x); }
; template <bool MASKED, class MF>
; DI void flash_update(f32x4 (&s)[4], float scl, float& mx, float& ls, f32x4 (&o)[8], MF maskfn, bool lane_on) {
;   float tmax = -1e30f;
; #pragma unroll
;   for (int kt = 0; kt < 4; ++kt)
; #pragma unroll
;     for (int i = 0; i < 4; ++i) {
;       if (MASKED) { if (maskfn(kt, i)) s[kt][i] = -1e30f; }
;       tmax = fmaxf(tmax, s[kt][i]);
;     }
;   tmax = rowmax4(tmax);
;   if (!lane_on) tmax = -1e30f;
;   const float th = 8.f / scl;
;   if (__any(tmax > mx + th)) {
;     const float mnew = fmaxf(mx, tmax);
;     const float alpha = ex2((mx - mnew) * scl);
;     ls *= alpha;
; #pragma unroll
;     for (int dt = 0; dt < 8; ++dt) o[dt] *= alpha;
;     mx = mnew;
;   }
.LBB0_584:
	v_cmp_le_u32_e32 vcc, v16, v209
	v_cmp_gt_u32_e64 s[6:7], v18, v209
	v_cmp_gt_u32_e64 s[8:9], v19, v209
	v_cndmask_b32_e32 v160, v195, v156, vcc
	v_cmp_lt_u32_e32 vcc, v16, v209
	v_cndmask_b32_e64 v18, v158, v195, s[6:7]
	v_cndmask_b32_e64 v19, v159, v195, s[8:9]
	v_cndmask_b32_e32 v16, v160, v156, vcc
	v_cndmask_b32_e32 v17, v195, v157, vcc
	v_cmp_gt_u32_e32 vcc, v21, v209
	v_max3_f32 v20, v160, s53, v17
	v_max3_f32 v156, v20, v18, v19
	v_cndmask_b32_e32 v21, v149, v195, vcc
	v_cmp_gt_u32_e32 vcc, v22, v209
	v_cndmask_b32_e64 v20, v148, v195, s[4:5]
	v_cmp_gt_u32_e64 s[4:5], v23, v209
	v_cndmask_b32_e32 v22, v150, v195, vcc
	v_cmp_le_u32_e32 vcc, v24, v209
	v_max3_f32 v148, v156, v20, v21
	v_cndmask_b32_e64 v23, v151, v195, s[4:5]
	v_cndmask_b32_e32 v24, v195, v152, vcc
	v_cmp_gt_u32_e32 vcc, v25, v209
	v_max3_f32 v148, v148, v22, v23
	v_cmp_gt_u32_e64 s[10:11], v27, v209
	v_cndmask_b32_e32 v25, v153, v195, vcc
	v_cmp_gt_u32_e32 vcc, v26, v209
	v_max3_f32 v148, v148, v24, v25
	v_cndmask_b32_e64 v27, v155, v195, s[10:11]
	v_cndmask_b32_e32 v26, v154, v195, vcc
	v_cmp_le_u32_e32 vcc, v28, v209
	v_max3_f32 v148, v148, v26, v27
	v_cmp_gt_u32_e64 s[12:13], v31, v209
	v_cndmask_b32_e32 v28, v195, v144, vcc
	v_cmp_gt_u32_e32 vcc, v29, v209
	v_cndmask_b32_e64 v31, v147, v195, s[12:13]
	s_nop 0
	v_cndmask_b32_e32 v29, v145, v195, vcc
	v_cmp_gt_u32_e32 vcc, v30, v209
	v_max3_f32 v144, v148, v28, v29
	s_nop 0
	v_cndmask_b32_e32 v30, v146, v195, vcc
	v_max3_f32 v144, v144, v30, v31
	v_mov_b32_e32 v145, v144
	s_nop 1
	v_permlane16_swap_b32_e32 v144, v145
	v_max_f32_e32 v144, v144, v145
	v_mov_b32_e32 v145, v144
	s_nop 1
	v_permlane32_swap_b32_e32 v144, v145
	v_max_f32_e32 v144, v144, v145
	v_add_f32_e32 v145, 0x40b17218, v221
	v_cmp_gt_f32_e32 vcc, v144, v145
	s_cbranch_vccnz .LBB0_567
	s_or_b64 vcc, s[8:9], s[6:7]
	v_cndmask_b32_e32 v16, v160, v16, vcc
	s_branch .LBB0_568

; #define SB0 __builtin_amdgcn_sched_barrier(0)
; DI void nsa_S(f32x4 (&s)[4], const char* Kb, const char* Vb, const bf16x8 (&qf)[4], bf16x8 (&v0)[4], int lr, int quad) {
;   bf16x8 k0[4], k1[4], k2[4], k3[4];
;   ldk4(k0, Kb, 0, lr, quad); SB0;
;   ldk4(k1, Kb, 1, lr, quad); s[0] = mma4(k0, qf); SB0;
;   ldk4(k2, Kb, 2, lr, quad); s[1] = mma4(k1, qf); SB0;
;   ldk4(k3, Kb, 3, lr, quad); s[2] = mma4(k2, qf); SB0;
;   ldv4(v0, Vb, 0, lr, quad); s[3] = mma4(k3, qf); SB0;
; }
.LBB0_752:
	v_lshl_add_u32 v14, s13, 15, v9
	v_add_u32_e32 v15, v14, v235
	v_add_u32_e32 v67, v14, v237
	v_add_u32_e32 v66, v14, v236
	ds_read_b128 v[10:13], v15
	ds_read_b128 v[34:37], v66
	v_add_u32_e32 v14, v14, v238
	ds_read_b128 v[38:41], v67
	ds_read_b128 v[42:45], v14
	s_xor_b64 s[10:11], s[10:11], -1
	ds_read_b128 v[46:49], v15 offset:4096
	ds_read_b128 v[50:53], v66 offset:4096
	ds_read_b128 v[54:57], v67 offset:4096
	ds_read_b128 v[58:61], v14 offset:4096
	s_waitcnt lgkmcnt(7)
	v_mfma_f32_16x16x32_bf16 v[10:13], v[10:13], v[18:21], 0
	s_waitcnt lgkmcnt(6)
	v_mfma_f32_16x16x32_bf16 v[10:13], v[34:37], v[22:25], v[10:13]
	s_waitcnt lgkmcnt(5)
	v_mfma_f32_16x16x32_bf16 v[10:13], v[38:41], v[26:29], v[10:13]
	s_waitcnt lgkmcnt(4)
	v_mfma_f32_16x16x32_bf16 v[10:13], v[42:45], v[30:33], v[10:13]
	s_nop 0
	ds_read_b128 v[34:37], v15 offset:8192
	ds_read_b128 v[38:41], v66 offset:8192
	ds_read_b128 v[42:45], v67 offset:8192
	ds_read_b128 v[62:65], v14 offset:8192
	s_waitcnt lgkmcnt(7)
	v_mfma_f32_16x16x32_bf16 v[46:49], v[46:49], v[18:21], 0
	s_waitcnt lgkmcnt(6)
	v_mfma_f32_16x16x32_bf16 v[46:49], v[50:53], v[22:25], v[46:49]
	s_waitcnt lgkmcnt(5)
	v_mfma_f32_16x16x32_bf16 v[46:49], v[54:57], v[26:29], v[46:49]
	s_waitcnt lgkmcnt(4)
	v_mfma_f32_16x16x32_bf16 v[46:49], v[58:61], v[30:33], v[46:49]
	s_nop 0
	ds_read_b128 v[50:53], v15 offset:12288
	ds_read_b128 v[54:57], v66 offset:12288
	ds_read_b128 v[58:61], v67 offset:12288
	ds_read_b128 v[66:69], v14 offset:12288
	s_waitcnt lgkmcnt(7)
	v_mfma_f32_16x16x32_bf16 v[34:37], v[34:37], v[18:21], 0
	s_waitcnt lgkmcnt(6)
	v_mfma_f32_16x16x32_bf16 v[34:37], v[38:41], v[22:25], v[34:37]
	s_waitcnt lgkmcnt(5)
	v_mfma_f32_16x16x32_bf16 v[34:37], v[42:45], v[26:29], v[34:37]
	s_waitcnt lgkmcnt(4)
	v_mfma_f32_16x16x32_bf16 v[34:37], v[62:65], v[30:33], v[34:37]
	s_nop 0
	s_waitcnt lgkmcnt(3)
	v_mfma_f32_16x16x32_bf16 v[38:41], v[50:53], v[18:21], 0
	s_waitcnt lgkmcnt(2)
	v_mfma_f32_16x16x32_bf16 v[38:41], v[54:57], v[22:25], v[38:41]
	s_waitcnt lgkmcnt(1)
	v_mfma_f32_16x16x32_bf16 v[38:41], v[58:61], v[26:29], v[38:41]
	s_waitcnt lgkmcnt(0)
; DI float ex2(float x) { return __builtin_amdgcn_exp2f(x); }
; DI void nsa_item(const Params& p, int b, int g, int qb, char* smem, int tid) {
;     ...
;     float tmax = -1e30f;
; #pragma unroll
;     for (int kt = 0; kt < 4; ++kt)
; #pragma unroll
;       for (int i = 0; i < 4; ++i) {
;         int cc = j * 64 + kt * 16 + quad * 4 + i;
;         float v = (cc <= cmax) ? s[kt][i] * SCL : -1e30f;
;         s[kt][i] = v; tmax = fmaxf(tmax, v);
;       }
;     tmax = rowmax4(tmax);
;     float mnew = fmaxf(mx, tmax), rs = 0.f;
; #pragma unroll
;     for (int kt = 0; kt < 4; ++kt)
; #pragma unroll
;       for (int i = 0; i < 4; ++i) { float v = s[kt][i]; rs += (v > -1e29f) ? ex2(v - mnew) : 0.f; }
;     ls = ls * ex2(mx - mnew) + rs; mx = mnew;
	v_mfma_f32_16x16x32_bf16 v[38:41], v[66:69], v[30:33], v[38:41]
	s_nop 0
	v_lshl_or_b32 v14, s12, 6, v214
	v_mul_f32_e32 v10, 0x3e0293ee, v10
	v_cmp_le_i32_e32 vcc, v14, v78
	v_mul_f32_e32 v11, 0x3e0293ee, v11
	v_or_b32_e32 v15, 2, v14
	v_cndmask_b32_e32 v10, v231, v10, vcc
	v_cmp_lt_i32_e32 vcc, v14, v78
	v_mul_f32_e32 v12, 0x3e0293ee, v12
	v_mul_f32_e32 v13, 0x3e0293ee, v13
	v_cndmask_b32_e32 v11, v231, v11, vcc
	v_cmp_le_i32_e32 vcc, v15, v78
	v_or_b32_e32 v15, 3, v14
	v_mul_f32_e32 v42, 0x3e0293ee, v46
	v_cndmask_b32_e32 v12, v231, v12, vcc
	v_cmp_le_i32_e32 vcc, v15, v78
	v_or_b32_e32 v15, 16, v14
	v_mul_f32_e32 v43, 0x3e0293ee, v47
	v_cndmask_b32_e32 v13, v231, v13, vcc
	v_cmp_le_i32_e32 vcc, v15, v78
	v_mul_f32_e32 v44, 0x3e0293ee, v48
	v_mul_f32_e32 v45, 0x3e0293ee, v49
	v_cndmask_b32_e32 v15, v231, v42, vcc
	v_or_b32_e32 v42, 17, v14
	v_cmp_le_i32_e32 vcc, v42, v78
	v_mul_f32_e32 v34, 0x3e0293ee, v34
	v_mul_f32_e32 v35, 0x3e0293ee, v35
	v_cndmask_b32_e32 v42, v231, v43, vcc
	v_or_b32_e32 v43, 18, v14
	v_cmp_le_i32_e32 vcc, v43, v78
	v_mul_f32_e32 v36, 0x3e0293ee, v36
	v_mul_f32_e32 v37, 0x3e0293ee, v37
	v_cndmask_b32_e32 v43, v231, v44, vcc
	v_or_b32_e32 v44, 19, v14
	v_cmp_le_i32_e32 vcc, v44, v78
	v_mul_f32_e32 v38, 0x3e0293ee, v38
	v_mul_f32_e32 v39, 0x3e0293ee, v39
	v_cndmask_b32_e32 v44, v231, v45, vcc
	v_or_b32_e32 v45, 32, v14
	v_cmp_le_i32_e32 vcc, v45, v78
	v_or_b32_e32 v45, 33, v14
	v_mul_f32_e32 v40, 0x3e0293ee, v40
	v_cndmask_b32_e32 v34, v231, v34, vcc
	v_cmp_le_i32_e32 vcc, v45, v78
	v_or_b32_e32 v45, 34, v14
	v_mul_f32_e32 v41, 0x3e0293ee, v41
	v_cndmask_b32_e32 v35, v231, v35, vcc
	v_cmp_le_i32_e32 vcc, v45, v78
	v_or_b32_e32 v45, 35, v14
	s_nop 0
	v_cndmask_b32_e32 v36, v231, v36, vcc
	v_cmp_le_i32_e32 vcc, v45, v78
	v_or_b32_e32 v45, 48, v14
	s_nop 0
	v_cndmask_b32_e32 v37, v231, v37, vcc
	v_cmp_le_i32_e32 vcc, v45, v78
	v_or_b32_e32 v45, 49, v14
	s_nop 0
	v_cndmask_b32_e32 v38, v231, v38, vcc
	v_cmp_le_i32_e32 vcc, v45, v78
	v_or_b32_e32 v45, 50, v14
	v_or_b32_e32 v14, 51, v14
	v_cndmask_b32_e32 v39, v231, v39, vcc
	v_cmp_le_i32_e32 vcc, v45, v78
	s_nop 1
	v_cndmask_b32_e32 v40, v231, v40, vcc
	v_cmp_le_i32_e32 vcc, v14, v78
	s_nop 1
	v_cndmask_b32_e32 v14, v231, v41, vcc
	v_max3_f32 v41, v10, s41, v11
	v_max3_f32 v41, v41, v12, v13
	v_max3_f32 v41, v41, v15, v42
	v_max3_f32 v41, v41, v43, v44
	v_max3_f32 v41, v41, v34, v35
	v_max3_f32 v41, v41, v36, v37
	v_max3_f32 v41, v41, v38, v39
	v_max3_f32 v41, v41, v40, v14
	v_mov_b32_e32 v45, v41
	s_nop 1
	v_permlane16_swap_b32_e32 v41, v45
	v_max_f32_e32 v41, v41, v45
	v_mov_b32_e32 v45, v41
	s_nop 1
	v_permlane32_swap_b32_e32 v41, v45
	v_max3_f32 v41, v94, v41, v45
	v_sub_f32_e32 v45, v10, v41
	v_exp_f32_e32 v45, v45
	v_cmp_lt_f32_e32 vcc, s33, v10
	v_sub_f32_e32 v46, v12, v41
	v_exp_f32_e32 v46, v46
	v_add_f32_e32 v45, 0, v45
	v_cndmask_b32_e32 v10, 0, v45, vcc
	v_sub_f32_e32 v45, v11, v41
	v_exp_f32_e32 v45, v45
	v_cmp_lt_f32_e32 vcc, s33, v11
	s_nop 1
	v_cndmask_b32_e32 v11, 0, v45, vcc
	v_cmp_lt_f32_e32 vcc, s33, v12
	v_add_f32_e32 v10, v11, v10
	v_sub_f32_e32 v12, v15, v41
	v_cndmask_b32_e32 v11, 0, v46, vcc
	v_add_f32_e32 v10, v11, v10
	v_sub_f32_e32 v11, v13, v41
	v_exp_f32_e32 v11, v11
	v_exp_f32_e32 v12, v12
	v_cmp_lt_f32_e32 vcc, s33, v13
	s_nop 1
	v_cndmask_b32_e32 v11, 0, v11, vcc
	v_cmp_lt_f32_e32 vcc, s33, v15
	v_add_f32_e32 v10, v11, v10
	s_nop 0
	v_cndmask_b32_e32 v11, 0, v12, vcc
	v_add_f32_e32 v10, v11, v10
	v_sub_f32_e32 v11, v42, v41
	v_exp_f32_e32 v11, v11
	v_sub_f32_e32 v12, v43, v41
	v_exp_f32_e32 v12, v12
	v_cmp_lt_f32_e32 vcc, s33, v42
	s_nop 1
	v_cndmask_b32_e32 v11, 0, v11, vcc
	v_cmp_lt_f32_e32 vcc, s33, v43
	v_add_f32_e32 v10, v11, v10
	s_nop 0
	v_cndmask_b32_e32 v11, 0, v12, vcc
	v_add_f32_e32 v10, v11, v10
	v_sub_f32_e32 v11, v44, v41
	v_exp_f32_e32 v11, v11
	v_sub_f32_e32 v12, v34, v41
	v_exp_f32_e32 v12, v12
	v_cmp_lt_f32_e32 vcc, s33, v44
	s_nop 1
	v_cndmask_b32_e32 v11, 0, v11, vcc
	v_cmp_lt_f32_e32 vcc, s33, v34
	v_add_f32_e32 v10, v11, v10
	s_nop 0
	v_cndmask_b32_e32 v11, 0, v12, vcc
	v_add_f32_e32 v10, v11, v10
	v_sub_f32_e32 v11, v35, v41
	v_exp_f32_e32 v11, v11
	v_sub_f32_e32 v12, v36, v41
	v_exp_f32_e32 v12, v12
	v_cmp_lt_f32_e32 vcc, s33, v35
	s_nop 1
	v_cndmask_b32_e32 v11, 0, v11, vcc
	v_cmp_lt_f32_e32 vcc, s33, v36
	v_add_f32_e32 v10, v11, v10
	s_nop 0
	v_cndmask_b32_e32 v11, 0, v12, vcc
	v_add_f32_e32 v10, v11, v10
	v_sub_f32_e32 v11, v37, v41
	v_exp_f32_e32 v11, v11
	v_sub_f32_e32 v12, v38, v41
	v_exp_f32_e32 v12, v12
	v_cmp_lt_f32_e32 vcc, s33, v37
	s_nop 1
	v_cndmask_b32_e32 v11, 0, v11, vcc
	v_cmp_lt_f32_e32 vcc, s33, v38
	v_add_f32_e32 v10, v11, v10
	s_nop 0
	v_cndmask_b32_e32 v11, 0, v12, vcc
	v_add_f32_e32 v10, v11, v10
	v_sub_f32_e32 v11, v39, v41
	v_exp_f32_e32 v11, v11
	v_sub_f32_e32 v12, v40, v41
	v_exp_f32_e32 v12, v12
	v_cmp_lt_f32_e32 vcc, s33, v39
	s_nop 1
	v_cndmask_b32_e32 v11, 0, v11, vcc
	v_cmp_lt_f32_e32 vcc, s33, v40
	v_add_f32_e32 v10, v11, v10
	s_nop 0
	v_cndmask_b32_e32 v11, 0, v12, vcc
	v_add_f32_e32 v10, v11, v10
	v_sub_f32_e32 v11, v14, v41
	v_exp_f32_e32 v11, v11
	v_sub_f32_e32 v12, v94, v41
	v_exp_f32_e32 v12, v12
	v_cmp_lt_f32_e32 vcc, s33, v14
	v_mov_b32_e32 v94, v41
	s_nop 0
	v_cndmask_b32_e32 v11, 0, v11, vcc
	v_add_f32_e32 v10, v11, v10
	v_fmac_f32_e32 v10, v7, v12
	v_mov_b32_e32 v7, v10
	s_mov_b32 s13, 1
	s_andn2_b64 vcc, exec, s[10:11]
	s_mov_b64 s[10:11], 0
	s_cbranch_vccz .LBB0_755

; DI float ex2(float x) { return __builtin_amdgcn_exp2f(x); }
; #define SB0 __builtin_amdgcn_sched_barrier(0)
; DI void nsa_S(f32x4 (&s)[4], const char* Kb, const char* Vb, const bf16x8 (&qf)[4], bf16x8 (&v0)[4], int lr, int quad) {
;   bf16x8 k0[4], k1[4], k2[4], k3[4];
;   ldk4(k0, Kb, 0, lr, quad); SB0;
;   ldk4(k1, Kb, 1, lr, quad); s[0] = mma4(k0, qf); SB0;
;   ldk4(k2, Kb, 2, lr, quad); s[1] = mma4(k1, qf); SB0;
;   ldk4(k3, Kb, 3, lr, quad); s[2] = mma4(k2, qf); SB0;
;   ldv4(v0, Vb, 0, lr, quad); s[3] = mma4(k3, qf); SB0;
; }
; template <bool MASKED, class MF>
; DI void flash_update(f32x4 (&s)[4], float scl, float& mx, float& ls, f32x4 (&o)[8], MF maskfn, bool lane_on) {
;   float tmax = -1e30f;
; #pragma unroll
;   for (int kt = 0; kt < 4; ++kt)
; #pragma unroll
;     for (int i = 0; i < 4; ++i) {
;       if (MASKED) { if (maskfn(kt, i)) s[kt][i] = -1e30f; }
;       tmax = fmaxf(tmax, s[kt][i]);
;     }
;   tmax = rowmax4(tmax);
;   if (!lane_on) tmax = -1e30f;
;   const float th = 8.f / scl;
;   if (__any(tmax > mx + th)) {
;     const float mnew = fmaxf(mx, tmax);
;     const float alpha = ex2((mx - mnew) * scl);
;     ls *= alpha;
; #pragma unroll
;     for (int dt = 0; dt < 8; ++dt) o[dt] *= alpha;
;     mx = mnew;
;   }
.LBB0_817:
	s_or_b32 s59, s48, s56
	s_cmp_gt_u32 s59, s2
	s_cbranch_scc1 .LBB0_816
	s_and_b32 s38, s59, 31
	s_waitcnt lgkmcnt(0)
	v_mov_b32_e32 v0, v172
	v_lshrrev_b32_e32 v1, s59, v0
	v_bfe_u32 v0, v0, s38, 1
	v_and_b32_e32 v1, 1, v1
	v_cmp_ne_u32_e32 vcc, 0, v0
	v_cmp_eq_u32_e64 s[38:39], 1, v1
	s_cbranch_vccz .LBB0_829
	s_lshl_b32 s48, s48, 15
	s_add_i32 s58, s57, s48
	v_add_u32_e32 v8, s58, v234
	v_add_u32_e32 v122, v8, v235
	v_add_u32_e32 v124, v8, v237
	v_add_u32_e32 v123, v8, v236
	ds_read_b128 v[0:3], v122
	ds_read_b128 v[4:7], v123
	v_add_u32_e32 v125, v8, v238
	ds_read_b128 v[8:11], v124
	ds_read_b128 v[12:15], v125
	ds_read_b128 v[98:101], v122 offset:4096
	ds_read_b128 v[102:105], v123 offset:4096
	ds_read_b128 v[106:109], v124 offset:4096
	ds_read_b128 v[110:113], v125 offset:4096
	s_waitcnt lgkmcnt(7)
	v_mfma_f32_16x16x32_bf16 v[142:145], v[0:3], v[18:21], 0
	s_waitcnt lgkmcnt(6)
	v_mfma_f32_16x16x32_bf16 v[142:145], v[4:7], v[22:25], v[142:145]
	s_waitcnt lgkmcnt(5)
	v_mfma_f32_16x16x32_bf16 v[142:145], v[8:11], v[26:29], v[142:145]
	s_waitcnt lgkmcnt(4)
	v_mfma_f32_16x16x32_bf16 v[114:117], v[12:15], v[30:33], v[142:145]
	ds_read_b128 v[0:3], v122 offset:8192
	ds_read_b128 v[4:7], v123 offset:8192
	ds_read_b128 v[8:11], v124 offset:8192
	ds_read_b128 v[12:15], v125 offset:8192
	s_waitcnt lgkmcnt(7)
	v_mfma_f32_16x16x32_bf16 v[98:101], v[98:101], v[18:21], 0
	s_waitcnt lgkmcnt(6)
	v_mfma_f32_16x16x32_bf16 v[98:101], v[102:105], v[22:25], v[98:101]
	s_waitcnt lgkmcnt(5)
	v_mfma_f32_16x16x32_bf16 v[98:101], v[106:109], v[26:29], v[98:101]
	s_waitcnt lgkmcnt(4)
	v_mfma_f32_16x16x32_bf16 v[118:121], v[110:113], v[30:33], v[98:101]
	s_nop 0
	ds_read_b128 v[126:129], v122 offset:12288
	ds_read_b128 v[130:133], v123 offset:12288
	ds_read_b128 v[134:137], v124 offset:12288
	ds_read_b128 v[138:141], v125 offset:12288
	s_waitcnt lgkmcnt(7)
	v_mfma_f32_16x16x32_bf16 v[142:145], v[0:3], v[18:21], 0
	s_waitcnt lgkmcnt(6)
	v_mfma_f32_16x16x32_bf16 v[142:145], v[4:7], v[22:25], v[142:145]
	s_waitcnt lgkmcnt(5)
	v_mfma_f32_16x16x32_bf16 v[142:145], v[8:11], v[26:29], v[142:145]
	s_waitcnt lgkmcnt(4)
	v_mfma_f32_16x16x32_bf16 v[122:125], v[12:15], v[30:33], v[142:145]
	v_add_u32_e32 v0, s58, v242
	v_add_u32_e32 v174, v0, v241
	ds_read_b128 v[98:101], v174 offset:16384
	ds_read_b128 v[102:105], v174 offset:18432
	ds_read_b128 v[106:109], v174 offset:20480
	ds_read_b128 v[110:113], v174 offset:22528
	s_waitcnt lgkmcnt(7)
	v_mfma_f32_16x16x32_bf16 v[0:3], v[126:129], v[18:21], 0
	s_waitcnt lgkmcnt(6)
	v_mfma_f32_16x16x32_bf16 v[0:3], v[130:133], v[22:25], v[0:3]
	s_waitcnt lgkmcnt(5)
	v_mfma_f32_16x16x32_bf16 v[0:3], v[134:137], v[26:29], v[0:3]
	s_waitcnt lgkmcnt(4)
	v_mfma_f32_16x16x32_bf16 v[126:129], v[138:141], v[30:33], v[0:3]
	s_nop 0
	s_mov_b64 s[48:49], -1
	s_cmp_lg_u32 s59, s2
	v_add_f32_e32 v176, 0x427af232, v173
	s_cbranch_scc0 .LBB0_823
	s_nop 1
	v_max3_f32 v0, v114, s41, v115
	v_max3_f32 v0, v0, v116, v117
	v_max3_f32 v0, v0, v118, v119
	v_max3_f32 v0, v0, v120, v121
	v_max3_f32 v0, v0, v122, v123
	v_max3_f32 v0, v0, v124, v125
	v_max3_f32 v0, v0, v126, v127
	v_max3_f32 v0, v0, v128, v129
	v_mov_b32_e32 v1, v0
	s_nop 1
	v_permlane16_swap_b32_e32 v0, v1
	v_max_f32_e32 v0, v0, v1
	v_mov_b32_e32 v1, v0
	s_nop 1
	v_permlane32_swap_b32_e32 v0, v1
	v_max_f32_e32 v0, v0, v1
	v_cndmask_b32_e64 v0, v231, v0, s[38:39]
	v_mov_b64_e32 v[160:161], v[68:69]
	v_mov_b64_e32 v[156:157], v[72:73]
	v_mov_b64_e32 v[152:153], v[76:77]
	v_mov_b64_e32 v[148:149], v[80:81]
	v_mov_b64_e32 v[144:145], v[84:85]
	v_mov_b64_e32 v[140:141], v[88:89]
	v_mov_b64_e32 v[136:137], v[92:93]
	v_mov_b64_e32 v[132:133], v[96:97]
	v_cmp_gt_f32_e32 vcc, v0, v176
	v_mov_b64_e32 v[158:159], v[66:67]
	v_mov_b64_e32 v[154:155], v[70:71]
	v_mov_b64_e32 v[150:151], v[74:75]
	v_mov_b64_e32 v[146:147], v[78:79]
	v_mov_b64_e32 v[142:143], v[82:83]
	v_mov_b64_e32 v[138:139], v[86:87]
	v_mov_b64_e32 v[134:135], v[90:91]
	v_mov_b64_e32 v[130:131], v[94:95]
	v_mov_b32_e32 v177, v170
	v_mov_b32_e32 v175, v173
	s_cbranch_vccz .LBB0_822
	v_max_f32_e32 v0, v0, v0
	v_max_f32_e32 v1, v173, v173
	v_max_f32_e32 v175, v1, v0
	v_sub_f32_e32 v0, v173, v175
	v_mul_f32_e32 v0, 0x3e0293ee, v0
	v_exp_f32_e32 v0, v0
	s_nop 0
	v_mul_f32_e32 v177, v170, v0
	v_pk_mul_f32 v[132:133], v[96:97], v[0:1] op_sel_hi:[1,0]
	v_pk_mul_f32 v[130:131], v[94:95], v[0:1] op_sel_hi:[1,0]
	v_pk_mul_f32 v[136:137], v[92:93], v[0:1] op_sel_hi:[1,0]
	v_pk_mul_f32 v[134:135], v[90:91], v[0:1] op_sel_hi:[1,0]
	v_pk_mul_f32 v[140:141], v[88:89], v[0:1] op_sel_hi:[1,0]
	v_pk_mul_f32 v[138:139], v[86:87], v[0:1] op_sel_hi:[1,0]
	v_pk_mul_f32 v[144:145], v[84:85], v[0:1] op_sel_hi:[1,0]
	v_pk_mul_f32 v[142:143], v[82:83], v[0:1] op_sel_hi:[1,0]
	v_pk_mul_f32 v[148:149], v[80:81], v[0:1] op_sel_hi:[1,0]
	v_pk_mul_f32 v[146:147], v[78:79], v[0:1] op_sel_hi:[1,0]
	v_pk_mul_f32 v[152:153], v[76:77], v[0:1] op_sel_hi:[1,0]
	v_pk_mul_f32 v[150:151], v[74:75], v[0:1] op_sel_hi:[1,0]
	v_pk_mul_f32 v[156:157], v[72:73], v[0:1] op_sel_hi:[1,0]
	v_pk_mul_f32 v[154:155], v[70:71], v[0:1] op_sel_hi:[1,0]
	v_pk_mul_f32 v[160:161], v[68:69], v[0:1] op_sel_hi:[1,0]
	v_pk_mul_f32 v[158:159], v[66:67], v[0:1] op_sel_hi:[1,0]

; DI float ex2(float x) { return __builtin_amdgcn_exp2f(x); }
; template <bool MASKED, class MF>
; DI void flash_update(f32x4 (&s)[4], float scl, float& mx, float& ls, f32x4 (&o)[8], MF maskfn, bool lane_on) {
;   float tmax = -1e30f;
; #pragma unroll
;   for (int kt = 0; kt < 4; ++kt)
; #pragma unroll
;     for (int i = 0; i < 4; ++i) {
;       if (MASKED) { if (maskfn(kt, i)) s[kt][i] = -1e30f; }
;       tmax = fmaxf(tmax, s[kt][i]);
;     }
;   tmax = rowmax4(tmax);
;   if (!lane_on) tmax = -1e30f;
;   const float th = 8.f / scl;
;   if (__any(tmax > mx + th)) {
;     const float mnew = fmaxf(mx, tmax);
;     const float alpha = ex2((mx - mnew) * scl);
;     ls *= alpha;
; #pragma unroll
;     for (int dt = 0; dt < 8; ++dt) o[dt] *= alpha;
;     mx = mnew;
;   }
.LBB0_823:
	s_and_b64 vcc, exec, s[48:49]
	s_cbranch_vccz .LBB0_828
	v_cndmask_b32_e64 v130, v114, v231, s[4:5]
	v_cndmask_b32_e64 v1, v231, v115, s[6:7]
	v_max3_f32 v4, v130, s41, v1
	v_cndmask_b32_e64 v2, v116, v231, s[8:9]
	v_cndmask_b32_e64 v3, v117, v231, s[10:11]
	v_max3_f32 v6, v4, v2, v3
	v_cndmask_b32_e64 v4, v118, v231, s[12:13]
	v_cndmask_b32_e64 v5, v119, v231, s[14:15]
	v_max3_f32 v8, v6, v4, v5
	v_cndmask_b32_e64 v6, v120, v231, s[16:17]
	v_cndmask_b32_e64 v7, v121, v231, s[18:19]
	v_max3_f32 v10, v8, v6, v7
	v_cndmask_b32_e64 v8, v122, v231, s[20:21]
	v_cndmask_b32_e64 v9, v123, v231, s[22:23]
	v_max3_f32 v12, v10, v8, v9
	v_cndmask_b32_e64 v10, v124, v231, s[24:25]
	v_cndmask_b32_e64 v11, v125, v231, s[26:27]
	v_max3_f32 v14, v12, v10, v11
	v_cndmask_b32_e64 v12, v126, v231, s[28:29]
	v_cndmask_b32_e64 v13, v127, v231, s[30:31]
	v_cndmask_b32_e64 v0, v130, v114, s[6:7]
	v_max3_f32 v114, v14, v12, v13
	v_cndmask_b32_e64 v14, v128, v231, s[34:35]
	v_cndmask_b32_e64 v15, v129, v231, s[36:37]
	v_max3_f32 v114, v114, v14, v15
	v_mov_b32_e32 v115, v114
	s_nop 1
	v_permlane16_swap_b32_e32 v114, v115
	v_max_f32_e32 v114, v114, v115
	v_mov_b32_e32 v115, v114
	s_nop 1
	v_permlane32_swap_b32_e32 v114, v115
	v_max_f32_e32 v114, v114, v115
	v_cndmask_b32_e64 v114, v231, v114, s[38:39]
	v_cmp_gt_f32_e32 vcc, v114, v176
	s_cbranch_vccz .LBB0_826
	v_max_f32_e32 v7, v114, v114
	v_max_f32_e32 v11, v173, v173
	v_max_f32_e32 v115, v11, v7
	v_sub_f32_e32 v7, v173, v115
	v_mul_f32_e32 v7, 0x3e0293ee, v7
	v_exp_f32_e32 v114, v7
	v_cndmask_b32_e64 v3, v117, v231, s[10:11]
	v_cndmask_b32_e64 v7, v121, v231, s[18:19]
	v_cndmask_b32_e64 v11, v125, v231, s[26:27]
	v_cndmask_b32_e64 v15, v129, v231, s[36:37]
	v_mul_f32_e32 v170, v170, v114
	v_pk_mul_f32 v[96:97], v[96:97], v[114:115] op_sel_hi:[1,0]
	v_pk_mul_f32 v[94:95], v[94:95], v[114:115] op_sel_hi:[1,0]
	v_pk_mul_f32 v[92:93], v[92:93], v[114:115] op_sel_hi:[1,0]
	v_pk_mul_f32 v[90:91], v[90:91], v[114:115] op_sel_hi:[1,0]
	v_pk_mul_f32 v[88:89], v[88:89], v[114:115] op_sel_hi:[1,0]
	v_pk_mul_f32 v[86:87], v[86:87], v[114:115] op_sel_hi:[1,0]
	v_pk_mul_f32 v[84:85], v[84:85], v[114:115] op_sel_hi:[1,0]
	v_pk_mul_f32 v[82:83], v[82:83], v[114:115] op_sel_hi:[1,0]
	v_pk_mul_f32 v[80:81], v[80:81], v[114:115] op_sel_hi:[1,0]
	v_pk_mul_f32 v[78:79], v[78:79], v[114:115] op_sel_hi:[1,0]
	v_pk_mul_f32 v[76:77], v[76:77], v[114:115] op_sel_hi:[1,0]
	v_pk_mul_f32 v[74:75], v[74:75], v[114:115] op_sel_hi:[1,0]
	v_pk_mul_f32 v[72:73], v[72:73], v[114:115] op_sel_hi:[1,0]
	v_pk_mul_f32 v[70:71], v[70:71], v[114:115] op_sel_hi:[1,0]
	v_pk_mul_f32 v[68:69], v[68:69], v[114:115] op_sel_hi:[1,0]
	v_pk_mul_f32 v[66:67], v[66:67], v[114:115] op_sel_hi:[1,0]
	v_mov_b32_e32 v173, v115
	s_branch .LBB0_827

; #define SB0 __builtin_amdgcn_sched_barrier(0)
; DI void nsa_S(f32x4 (&s)[4], const char* Kb, const char* Vb, const bf16x8 (&qf)[4], bf16x8 (&v0)[4], int lr, int quad) {
;   bf16x8 k0[4], k1[4], k2[4], k3[4];
;   ldk4(k0, Kb, 0, lr, quad); SB0;
;   ldk4(k1, Kb, 1, lr, quad); s[0] = mma4(k0, qf); SB0;
;   ldk4(k2, Kb, 2, lr, quad); s[1] = mma4(k1, qf); SB0;
;   ldk4(k3, Kb, 3, lr, quad); s[2] = mma4(k2, qf); SB0;
;   ldv4(v0, Vb, 0, lr, quad); s[3] = mma4(k3, qf); SB0;
; }
; DI void nsa_item(const Params& p, int b, int g, int qb, char* smem, int tid) {
;     ...
;       auto mf = [&](int kt, int i) __attribute__((always_inline)) {
;         int key = j * 64 + kt * 16 + quad * 4 + i;
;         return (key > qp) || (key <= qp - 512);
;       };
;       if (j * 64 + 63 <= q0 && j * 64 > q0 + 31 - 512) flash_update<false>(s, SCL, mx2, l2, o, mf, true);
;       else flash_update<true>(s, SCL, mx2, l2, o, mf, true);
.LBB0_844:
	s_lshl_b32 s5, s6, 15
	s_add_i32 s24, s23, s5
	v_add_u32_e32 v8, s24, v234
	v_add_u32_e32 v146, v8, v235
	v_add_u32_e32 v151, v8, v237
	v_add_u32_e32 v150, v8, v236
	ds_read_b128 v[0:3], v146
	ds_read_b128 v[4:7], v150
	v_add_u32_e32 v152, v8, v238
	ds_read_b128 v[8:11], v151
	ds_read_b128 v[12:15], v152
	ds_read_b128 v[130:133], v146 offset:4096
	ds_read_b128 v[134:137], v150 offset:4096
	ds_read_b128 v[138:141], v151 offset:4096
	ds_read_b128 v[142:145], v152 offset:4096
	s_waitcnt lgkmcnt(7)
	v_mfma_f32_16x16x32_bf16 v[174:177], v[0:3], v[18:21], 0
	s_waitcnt lgkmcnt(6)
	v_mfma_f32_16x16x32_bf16 v[174:177], v[4:7], v[22:25], v[174:177]
	s_waitcnt lgkmcnt(5)
	v_mfma_f32_16x16x32_bf16 v[174:177], v[8:11], v[26:29], v[174:177]
	s_waitcnt lgkmcnt(4)
	v_mfma_f32_16x16x32_bf16 v[158:161], v[12:15], v[30:33], v[174:177]
	ds_read_b128 v[0:3], v146 offset:8192
	ds_read_b128 v[4:7], v150 offset:8192
	ds_read_b128 v[8:11], v151 offset:8192
	ds_read_b128 v[12:15], v152 offset:8192
	s_waitcnt lgkmcnt(7)
	v_mfma_f32_16x16x32_bf16 v[130:133], v[130:133], v[18:21], 0
	s_waitcnt lgkmcnt(6)
	v_mfma_f32_16x16x32_bf16 v[130:133], v[134:137], v[22:25], v[130:133]
	s_waitcnt lgkmcnt(5)
	v_mfma_f32_16x16x32_bf16 v[130:133], v[138:141], v[26:29], v[130:133]
	s_waitcnt lgkmcnt(4)
	v_mfma_f32_16x16x32_bf16 v[154:157], v[142:145], v[30:33], v[130:133]
	s_nop 0
	ds_read_b128 v[146:149], v146 offset:12288
	ds_read_b128 v[162:165], v150 offset:12288
	ds_read_b128 v[166:169], v151 offset:12288
	ds_read_b128 v[170:173], v152 offset:12288
	s_waitcnt lgkmcnt(7)
	v_mfma_f32_16x16x32_bf16 v[174:177], v[0:3], v[18:21], 0
	s_waitcnt lgkmcnt(6)
	v_mfma_f32_16x16x32_bf16 v[174:177], v[4:7], v[22:25], v[174:177]
	s_waitcnt lgkmcnt(5)
	v_mfma_f32_16x16x32_bf16 v[174:177], v[8:11], v[26:29], v[174:177]
	s_waitcnt lgkmcnt(4)
	v_mfma_f32_16x16x32_bf16 v[150:153], v[12:15], v[30:33], v[174:177]
	v_add_u32_e32 v0, s24, v242
	v_add_u32_e32 v247, v0, v241
	ds_read_b128 v[130:133], v247 offset:16384
	ds_read_b128 v[134:137], v247 offset:18432
	ds_read_b128 v[138:141], v247 offset:20480
	ds_read_b128 v[142:145], v247 offset:22528
	s_waitcnt lgkmcnt(7)
	v_mfma_f32_16x16x32_bf16 v[0:3], v[146:149], v[18:21], 0
	s_waitcnt lgkmcnt(6)
	v_mfma_f32_16x16x32_bf16 v[0:3], v[162:165], v[22:25], v[0:3]
	s_waitcnt lgkmcnt(5)
	v_mfma_f32_16x16x32_bf16 v[0:3], v[166:169], v[26:29], v[0:3]
	s_waitcnt lgkmcnt(4)
	v_mfma_f32_16x16x32_bf16 v[146:149], v[170:173], v[30:33], v[0:3]
	s_nop 0
	s_lshl_b32 s6, s4, 6
	s_or_b32 s4, s6, 63
	s_cmp_le_u32 s4, s85
	s_cselect_b64 s[4:5], -1, 0
	s_cmp_gt_i32 s6, s21
	s_cselect_b64 s[8:9], -1, 0
	s_and_b64 s[8:9], s[4:5], s[8:9]
	s_mov_b64 s[4:5], -1
	s_andn2_b64 vcc, exec, s[8:9]
	v_add_f32_e32 v249, 0x427af232, v246
	s_cbranch_vccz .LBB0_849
; DI float ex2(float x) { return __builtin_amdgcn_exp2f(x); }
; template <bool MASKED, class MF>
; DI void flash_update(f32x4 (&s)[4], float scl, float& mx, float& ls, f32x4 (&o)[8], MF maskfn, bool lane_on) {
;   float tmax = -1e30f;
; #pragma unroll
;   for (int kt = 0; kt < 4; ++kt)
; #pragma unroll
;     for (int i = 0; i < 4; ++i) {
;       if (MASKED) { if (maskfn(kt, i)) s[kt][i] = -1e30f; }
;       tmax = fmaxf(tmax, s[kt][i]);
;     }
;   tmax = rowmax4(tmax);
;   if (!lane_on) tmax = -1e30f;
;   const float th = 8.f / scl;
;   if (__any(tmax > mx + th)) {
;     const float mnew = fmaxf(mx, tmax);
;     const float alpha = ex2((mx - mnew) * scl);
;     ls *= alpha;
; #pragma unroll
;     for (int dt = 0; dt < 8; ++dt) o[dt] *= alpha;
;     mx = mnew;
;   }
	v_or_b32_e32 v15, s6, v214
	v_cmp_gt_i32_e32 vcc, v15, v233
	v_cmp_le_i32_e64 s[4:5], v15, v245
	s_or_b64 vcc, vcc, s[4:5]
	v_cndmask_b32_e32 v0, v158, v231, vcc
	v_cmp_ge_i32_e32 vcc, v15, v233
	v_cmp_lt_i32_e64 s[4:5], v15, v245
	s_or_b64 vcc, vcc, s[4:5]
	v_or_b32_e32 v2, 2, v15
	v_cndmask_b32_e32 v1, v159, v231, vcc
	v_cmp_gt_i32_e32 vcc, v2, v233
	v_cmp_le_i32_e64 s[4:5], v2, v245
	s_or_b64 vcc, vcc, s[4:5]
	v_or_b32_e32 v3, 3, v15
	v_cndmask_b32_e32 v2, v160, v231, vcc
	v_cmp_gt_i32_e32 vcc, v3, v233
	v_cmp_le_i32_e64 s[4:5], v3, v245
	s_or_b64 s[4:5], vcc, s[4:5]
	v_max3_f32 v4, v0, s41, v1
	v_cndmask_b32_e64 v3, v161, v231, s[4:5]
	v_max3_f32 v6, v4, v2, v3
	v_or_b32_e32 v4, 16, v15
	v_cmp_gt_i32_e32 vcc, v4, v233
	v_cmp_le_i32_e64 s[6:7], v4, v245
	s_or_b64 vcc, vcc, s[6:7]
	v_or_b32_e32 v5, 17, v15
	v_cndmask_b32_e32 v4, v154, v231, vcc
	v_cmp_gt_i32_e32 vcc, v5, v233
	v_cmp_le_i32_e64 s[6:7], v5, v245
	s_or_b64 vcc, vcc, s[6:7]
	v_cndmask_b32_e32 v5, v155, v231, vcc
	v_max3_f32 v8, v6, v4, v5
	v_or_b32_e32 v6, 18, v15
	v_cmp_gt_i32_e32 vcc, v6, v233
	v_cmp_le_i32_e64 s[6:7], v6, v245
	s_or_b64 vcc, vcc, s[6:7]
	v_or_b32_e32 v7, 19, v15
	v_cndmask_b32_e32 v6, v156, v231, vcc
	v_cmp_gt_i32_e32 vcc, v7, v233
	v_cmp_le_i32_e64 s[6:7], v7, v245
	s_or_b64 s[6:7], vcc, s[6:7]
	v_or_b32_e32 v9, 33, v15
	v_cndmask_b32_e64 v7, v157, v231, s[6:7]
	v_max3_f32 v10, v8, v6, v7
	v_or_b32_e32 v8, 32, v15
	v_cmp_gt_i32_e32 vcc, v8, v233
	v_cmp_le_i32_e64 s[8:9], v8, v245
	s_or_b64 vcc, vcc, s[8:9]
	v_cndmask_b32_e32 v8, v150, v231, vcc
	v_cmp_gt_i32_e32 vcc, v9, v233
	v_cmp_le_i32_e64 s[8:9], v9, v245
	s_or_b64 vcc, vcc, s[8:9]
	v_cndmask_b32_e32 v9, v151, v231, vcc
	v_max3_f32 v12, v10, v8, v9
	v_or_b32_e32 v10, 34, v15
	v_cmp_gt_i32_e32 vcc, v10, v233
	v_cmp_le_i32_e64 s[8:9], v10, v245
	s_or_b64 vcc, vcc, s[8:9]
	v_or_b32_e32 v11, 35, v15
	v_cndmask_b32_e32 v10, v152, v231, vcc
	v_cmp_gt_i32_e32 vcc, v11, v233
	v_cmp_le_i32_e64 s[8:9], v11, v245
	s_or_b64 s[8:9], vcc, s[8:9]
	v_or_b32_e32 v13, 49, v15
	v_cndmask_b32_e64 v11, v153, v231, s[8:9]
	v_max3_f32 v14, v12, v10, v11
	v_or_b32_e32 v12, 48, v15
	v_cmp_gt_i32_e32 vcc, v12, v233
	v_cmp_le_i32_e64 s[10:11], v12, v245
	s_or_b64 vcc, vcc, s[10:11]
	v_cndmask_b32_e32 v12, v146, v231, vcc
	v_cmp_gt_i32_e32 vcc, v13, v233
	v_cmp_le_i32_e64 s[10:11], v13, v245
	s_or_b64 vcc, vcc, s[10:11]
	v_cndmask_b32_e32 v13, v147, v231, vcc
	v_max3_f32 v162, v14, v12, v13
	v_or_b32_e32 v14, 50, v15
	v_cmp_gt_i32_e32 vcc, v14, v233
	v_cmp_le_i32_e64 s[10:11], v14, v245
	s_or_b64 vcc, vcc, s[10:11]
	v_or_b32_e32 v15, 51, v15
	v_cndmask_b32_e32 v14, v148, v231, vcc
	v_cmp_gt_i32_e32 vcc, v15, v233
	v_cmp_le_i32_e64 s[10:11], v15, v245
	s_or_b64 s[10:11], vcc, s[10:11]
	s_nop 0
	v_cndmask_b32_e64 v15, v149, v231, s[10:11]
	v_max3_f32 v162, v162, v14, v15
	v_mov_b32_e32 v163, v162
	s_nop 1
	v_permlane16_swap_b32_e32 v162, v163
	v_max_f32_e32 v162, v162, v163
	v_mov_b32_e32 v163, v162
	s_nop 1
	v_permlane32_swap_b32_e32 v162, v163
	v_max_f32_e32 v162, v162, v163
	v_cmp_gt_f32_e32 vcc, v162, v249
	s_cbranch_vccz .LBB0_847
	v_max_f32_e32 v7, v162, v162
	v_max_f32_e32 v11, v246, v246
	v_max_f32_e32 v248, v11, v7
	v_sub_f32_e32 v7, v246, v248
	v_mul_f32_e32 v7, 0x3e0293ee, v7
	v_exp_f32_e32 v190, v7
	v_cndmask_b32_e64 v3, v161, v231, s[4:5]
	v_cndmask_b32_e64 v7, v157, v231, s[6:7]
	v_cndmask_b32_e64 v11, v153, v231, s[8:9]
	v_cndmask_b32_e64 v15, v149, v231, s[10:11]
	v_mul_f32_e32 v250, v244, v190
	v_pk_mul_f32 v[164:165], v[128:129], v[190:191] op_sel_hi:[1,0]
	v_pk_mul_f32 v[162:163], v[126:127], v[190:191] op_sel_hi:[1,0]
	v_pk_mul_f32 v[168:169], v[124:125], v[190:191] op_sel_hi:[1,0]
	v_pk_mul_f32 v[166:167], v[122:123], v[190:191] op_sel_hi:[1,0]
	v_pk_mul_f32 v[172:173], v[120:121], v[190:191] op_sel_hi:[1,0]
	v_pk_mul_f32 v[170:171], v[118:119], v[190:191] op_sel_hi:[1,0]
	v_pk_mul_f32 v[176:177], v[116:117], v[190:191] op_sel_hi:[1,0]
	v_pk_mul_f32 v[174:175], v[114:115], v[190:191] op_sel_hi:[1,0]
	v_pk_mul_f32 v[180:181], v[112:113], v[190:191] op_sel_hi:[1,0]
	v_pk_mul_f32 v[178:179], v[110:111], v[190:191] op_sel_hi:[1,0]
	v_pk_mul_f32 v[184:185], v[108:109], v[190:191] op_sel_hi:[1,0]
	v_pk_mul_f32 v[182:183], v[106:107], v[190:191] op_sel_hi:[1,0]
	v_pk_mul_f32 v[188:189], v[104:105], v[190:191] op_sel_hi:[1,0]
	v_pk_mul_f32 v[186:187], v[102:103], v[190:191] op_sel_hi:[1,0]
	v_pk_mul_f32 v[192:193], v[100:101], v[190:191] op_sel_hi:[1,0]
	v_pk_mul_f32 v[190:191], v[98:99], v[190:191] op_sel_hi:[1,0]
	s_branch .LBB0_848

; DI float ex2(float x) { return __builtin_amdgcn_exp2f(x); }
; template <bool MASKED, class MF>
; DI void flash_update(f32x4 (&s)[4], float scl, float& mx, float& ls, f32x4 (&o)[8], MF maskfn, bool lane_on) {
;   float tmax = -1e30f;
; #pragma unroll
;   for (int kt = 0; kt < 4; ++kt)
; #pragma unroll
;     for (int i = 0; i < 4; ++i) {
;       if (MASKED) { if (maskfn(kt, i)) s[kt][i] = -1e30f; }
;       tmax = fmaxf(tmax, s[kt][i]);
;     }
;   tmax = rowmax4(tmax);
;   if (!lane_on) tmax = -1e30f;
;   const float th = 8.f / scl;
;   if (__any(tmax > mx + th)) {
;     const float mnew = fmaxf(mx, tmax);
;     const float alpha = ex2((mx - mnew) * scl);
;     ls *= alpha;
; #pragma unroll
;     for (int dt = 0; dt < 8; ++dt) o[dt] *= alpha;
;     mx = mnew;
;   }
.LBB0_849:
	s_and_b64 vcc, exec, s[4:5]
	s_cbranch_vccz .LBB0_853
	v_max3_f32 v0, v158, s41, v159
	v_max3_f32 v0, v0, v160, v161
	v_max3_f32 v0, v0, v154, v155
	v_max3_f32 v0, v0, v156, v157
	v_max3_f32 v0, v0, v150, v151
	v_max3_f32 v0, v0, v152, v153
	v_max3_f32 v0, v0, v146, v147
	v_max3_f32 v0, v0, v148, v149
	v_mov_b32_e32 v1, v0
	s_nop 1
	v_permlane16_swap_b32_e32 v0, v1
	v_max_f32_e32 v0, v0, v1
	v_mov_b32_e32 v1, v0
	s_nop 1
	v_permlane32_swap_b32_e32 v0, v1
	v_max_f32_e32 v0, v0, v1
	v_cmp_gt_f32_e32 vcc, v0, v249
	s_cbranch_vccz .LBB0_852
	v_max_f32_e32 v0, v0, v0
	v_max_f32_e32 v1, v246, v246
	v_max_f32_e32 v1, v1, v0
	v_sub_f32_e32 v0, v246, v1
	v_mul_f32_e32 v0, 0x3e0293ee, v0
	v_exp_f32_e32 v0, v0
	v_mov_b32_e32 v246, v1
	v_mul_f32_e32 v244, v244, v0
	v_pk_mul_f32 v[128:129], v[128:129], v[0:1] op_sel_hi:[1,0]
	v_pk_mul_f32 v[126:127], v[126:127], v[0:1] op_sel_hi:[1,0]
	v_pk_mul_f32 v[124:125], v[124:125], v[0:1] op_sel_hi:[1,0]
	v_pk_mul_f32 v[122:123], v[122:123], v[0:1] op_sel_hi:[1,0]
	v_pk_mul_f32 v[120:121], v[120:121], v[0:1] op_sel_hi:[1,0]
	v_pk_mul_f32 v[118:119], v[118:119], v[0:1] op_sel_hi:[1,0]
	v_pk_mul_f32 v[116:117], v[116:117], v[0:1] op_sel_hi:[1,0]
	v_pk_mul_f32 v[114:115], v[114:115], v[0:1] op_sel_hi:[1,0]
	v_pk_mul_f32 v[112:113], v[112:113], v[0:1] op_sel_hi:[1,0]
	v_pk_mul_f32 v[110:111], v[110:111], v[0:1] op_sel_hi:[1,0]
	v_pk_mul_f32 v[108:109], v[108:109], v[0:1] op_sel_hi:[1,0]
	v_pk_mul_f32 v[106:107], v[106:107], v[0:1] op_sel_hi:[1,0]
	v_pk_mul_f32 v[104:105], v[104:105], v[0:1] op_sel_hi:[1,0]
	v_pk_mul_f32 v[102:103], v[102:103], v[0:1] op_sel_hi:[1,0]
	v_pk_mul_f32 v[100:101], v[100:101], v[0:1] op_sel_hi:[1,0]
	v_pk_mul_f32 v[98:99], v[98:99], v[0:1] op_sel_hi:[1,0]
